# v11 + EpiResX: 7 row-sum bpermute chains batched, 4 slot loads in one round trip; post phase: spw loads batched, z-load wait moved after the batch; bit-identical
# speedup vs baseline: 1.0021x; 1.0021x over previous
; #define LAS __attribute__((address_space(3)))
; __device__ __forceinline__ unsigned pk2(float lo, float hi) { unsigned r; asm volatile("v_cvt_pk_bf16_f32 %0, %1, %2" : "=v"(r) : "v"(lo), "v"(hi)); return r; }
; __device__ __forceinline__ void post_phase(const Args& a, int li, LAS unsigned char* lds) {
;     ...
;             { const int cp = tid & 63, tp = tid >> 6; const int c0 = 128 * g + 2 * cp; const float g0 = bn_g[c0], g1 = bn_g[c0 + 1], b0 = bn_b[c0], b1 = bn_b[c0 + 1];
;               unsigned wa_[8], wb_[8];
; #pragma unroll
;               for (int it = 0; it < 8; ++it) { const int tt = tp + 8 * it; wa_[it] = *(const unsigned*)(proj + (t0 + 2 * tt) * P_EVEN + 2304 + c0); wb_[it] = *(const unsigned*)(proj + (t0 + 2 * tt + 1) * P_EVEN + 2304 + c0); }
; #pragma unroll
;               for (int it = 0; it < 8; ++it) { const int tt = tp + 8 * it; const unsigned wa = wa_[it], wb = wb_[it];
;                   const f32x2 sa = *(const LAS f32x2*)(lds + PZ_STAT + (2 * tt) * 8), sb = *(const LAS f32x2*)(lds + PZ_STAT + (2 * tt + 1) * 8);
;                   const float za0 = (bflo(wa) - sa.x) * sa.y * g0 + b0, za1 = (bfhi(wa) - sa.x) * sa.y * g1 + b1, zb0 = (bflo(wb) - sb.x) * sb.y * g0 + b0, zb1 = (bfhi(wb) - sb.x) * sb.y * g1 + b1;
;                   *(LAS unsigned*)(lds + PZ_ZT + (2 * cp) * 272 + (2 * tt) * 2) = pk2(za0, zb0); *(LAS unsigned*)(lds + PZ_ZT + (2 * cp + 1) * 272 + (2 * tt) * 2) = pk2(za1, zb1); } }
.LBB0_655:
	v_lshl_add_u64 v[4:5], s[24:25], 0, v[16:17]
	v_add_co_u32_e32 v6, vcc, 0xe001000, v4
	v_lshl_add_u64 v[0:1], v[124:125], 0, s[26:27]
	s_nop 0
	v_addc_co_u32_e32 v7, vcc, 0, v5, vcc
	flat_load_dword v8, v[6:7] offset:512
	v_add_co_u32_e32 v6, vcc, 0xe002000, v4
	v_lshl_add_u64 v[2:3], v[126:127], 0, s[26:27]
	s_nop 0
	v_addc_co_u32_e32 v7, vcc, 0, v5, vcc
	flat_load_dword v9, v[6:7] offset:2048
	v_add_co_u32_e32 v6, vcc, 0xe017000, v4
	global_load_dwordx2 v[0:1], v[0:1], off
	s_nop 0
	v_addc_co_u32_e32 v7, vcc, 0, v5, vcc
	global_load_dwordx2 v[2:3], v[2:3], off
	s_mov_b32 s2, 0x5b00000
	flat_load_dword v10, v[6:7] offset:512
	v_add_co_u32_e32 v6, vcc, 0xe018000, v4
	v_add_u32_e32 v69, v87, v93
	s_nop 0
	v_addc_co_u32_e32 v7, vcc, 0, v5, vcc
	flat_load_dword v11, v[6:7] offset:2048
	v_add_co_u32_e32 v6, vcc, 0xe02d000, v4
	v_lshl_add_u64 v[16:17], v[16:17], 0, s[12:13]
	s_nop 0
	v_addc_co_u32_e32 v7, vcc, 0, v5, vcc
	flat_load_dword v12, v[6:7] offset:512
	v_add_co_u32_e32 v6, vcc, 0xe02e000, v4
	s_nop 1
	v_addc_co_u32_e32 v7, vcc, 0, v5, vcc
	flat_load_dword v13, v[6:7] offset:2048
	v_add_co_u32_e32 v6, vcc, 0xe043000, v4
	s_nop 1
	v_addc_co_u32_e32 v7, vcc, 0, v5, vcc
	flat_load_dword v14, v[6:7] offset:512
	v_add_co_u32_e32 v6, vcc, 0xe044000, v4
	s_nop 1
	v_addc_co_u32_e32 v7, vcc, 0, v5, vcc
	flat_load_dword v15, v[6:7] offset:2048
	v_add_co_u32_e32 v6, vcc, 0xe059000, v4
	s_nop 1
	v_addc_co_u32_e32 v7, vcc, 0, v5, vcc
	flat_load_dword v37, v[6:7] offset:512
	v_add_co_u32_e32 v6, vcc, 0xe05a000, v4
	s_nop 1
	v_addc_co_u32_e32 v7, vcc, 0, v5, vcc
	flat_load_dword v40, v[6:7] offset:2048
	v_add_co_u32_e32 v6, vcc, 0xe06f000, v4
	s_nop 1
	v_addc_co_u32_e32 v7, vcc, 0, v5, vcc
	flat_load_dword v41, v[6:7] offset:512
	v_add_co_u32_e32 v6, vcc, 0xe070000, v4
	s_nop 1
	v_addc_co_u32_e32 v7, vcc, 0, v5, vcc
	flat_load_dword v42, v[6:7] offset:2048
	v_add_co_u32_e32 v6, vcc, 0xe085000, v4
	s_nop 1
	v_addc_co_u32_e32 v7, vcc, 0, v5, vcc
	flat_load_dword v43, v[6:7] offset:512
	v_add_co_u32_e32 v6, vcc, 0xe086000, v4
	s_nop 1
	v_addc_co_u32_e32 v7, vcc, 0, v5, vcc
	flat_load_dword v44, v[6:7] offset:2048
	v_add_co_u32_e32 v6, vcc, 0xe09b000, v4
	s_nop 1
	v_addc_co_u32_e32 v7, vcc, 0, v5, vcc
	v_add_co_u32_e32 v4, vcc, 0xe09c000, v4
	flat_load_dword v45, v[6:7] offset:512
	s_nop 0
	v_addc_co_u32_e32 v5, vcc, 0, v5, vcc
	flat_load_dword v46, v[4:5] offset:2048
	s_waitcnt vmcnt(0) lgkmcnt(0)
	v_lshlrev_b32_e32 v47, 16, v8
	v_and_b32_e32 v8, 0xffff0000, v8
	ds_read_b128 v[4:7], v99
	s_waitcnt lgkmcnt(0)
	v_sub_f32_e32 v47, v47, v4
	v_sub_f32_e32 v4, v8, v4
	v_mul_f32_e32 v47, v5, v47
	v_mul_f32_e32 v4, v5, v4
	v_lshlrev_b32_e32 v5, 16, v9
	v_sub_f32_e32 v5, v5, v6
	v_and_b32_e32 v8, 0xffff0000, v9
	v_mul_f32_e32 v5, v7, v5
	v_sub_f32_e32 v6, v8, v6
	v_fma_f32 v4, v1, v4, v3
	v_fma_f32 v5, v0, v5, v2
	v_mul_f32_e32 v6, v7, v6
	v_fma_f32 v47, v0, v47, v2
	v_fma_f32 v6, v1, v6, v3
	v_cvt_pk_bf16_f32 v5, v47, v5
	ds_write_b32 v214, v5 offset:1024
	v_cvt_pk_bf16_f32 v4, v4, v6
	ds_write_b32 v214, v4 offset:1296
	ds_read_b128 v[4:7], v215
	v_lshlrev_b32_e32 v8, 16, v10
	v_and_b32_e32 v9, 0xffff0000, v10
	s_waitcnt lgkmcnt(0)
	v_sub_f32_e32 v8, v8, v4
	v_sub_f32_e32 v4, v9, v4
	v_mul_f32_e32 v8, v5, v8
	v_mul_f32_e32 v4, v5, v4
	v_lshlrev_b32_e32 v5, 16, v11
	v_sub_f32_e32 v5, v5, v6
	v_and_b32_e32 v9, 0xffff0000, v11
	v_mul_f32_e32 v5, v7, v5
	v_sub_f32_e32 v6, v9, v6
	v_fma_f32 v4, v1, v4, v3
	v_fma_f32 v5, v0, v5, v2
	v_mul_f32_e32 v6, v7, v6
	v_fma_f32 v8, v0, v8, v2
	v_fma_f32 v6, v1, v6, v3
	v_cvt_pk_bf16_f32 v5, v8, v5
	ds_write_b32 v216, v5 offset:1024
	v_cvt_pk_bf16_f32 v4, v4, v6
	ds_write_b32 v216, v4 offset:1296
	ds_read_b128 v[4:7], v217
	v_lshlrev_b32_e32 v8, 16, v12
	v_and_b32_e32 v9, 0xffff0000, v12
	s_waitcnt lgkmcnt(0)
	v_sub_f32_e32 v8, v8, v4
	v_sub_f32_e32 v4, v9, v4
	v_mul_f32_e32 v8, v5, v8
	v_mul_f32_e32 v4, v5, v4
	s_waitcnt vmcnt(0)
	v_lshlrev_b32_e32 v5, 16, v13
	v_sub_f32_e32 v5, v5, v6
	v_and_b32_e32 v9, 0xffff0000, v13
	v_mul_f32_e32 v5, v7, v5
	v_sub_f32_e32 v6, v9, v6
	v_fma_f32 v4, v1, v4, v3
	v_fma_f32 v5, v0, v5, v2
	v_mul_f32_e32 v6, v7, v6
	v_fma_f32 v8, v0, v8, v2
	v_fma_f32 v6, v1, v6, v3
	v_cvt_pk_bf16_f32 v5, v8, v5
	ds_write_b32 v218, v5 offset:1024
	v_cvt_pk_bf16_f32 v4, v4, v6
	ds_write_b32 v218, v4 offset:1296
	ds_read_b128 v[4:7], v219
	v_lshlrev_b32_e32 v8, 16, v14
	v_and_b32_e32 v9, 0xffff0000, v14
	s_waitcnt lgkmcnt(0)
	v_sub_f32_e32 v8, v8, v4
	v_sub_f32_e32 v4, v9, v4
	v_mul_f32_e32 v8, v5, v8
	v_mul_f32_e32 v4, v5, v4
	v_lshlrev_b32_e32 v5, 16, v15
	v_sub_f32_e32 v5, v5, v6
	v_and_b32_e32 v9, 0xffff0000, v15
	v_mul_f32_e32 v5, v7, v5
	v_sub_f32_e32 v6, v9, v6
	v_fma_f32 v4, v1, v4, v3
	v_fma_f32 v5, v0, v5, v2
	v_mul_f32_e32 v6, v7, v6
	v_fma_f32 v8, v0, v8, v2
	v_fma_f32 v6, v1, v6, v3
	v_cvt_pk_bf16_f32 v5, v8, v5
	ds_write_b32 v220, v5 offset:1024
	v_cvt_pk_bf16_f32 v4, v4, v6
	ds_write_b32 v220, v4 offset:1296
	ds_read_b128 v[4:7], v221
	v_lshlrev_b32_e32 v8, 16, v37
	v_and_b32_e32 v9, 0xffff0000, v37
	v_ashrrev_i32_e32 v37, 31, v36
	s_waitcnt lgkmcnt(0)
	v_sub_f32_e32 v8, v8, v4
	v_sub_f32_e32 v4, v9, v4
	v_mul_f32_e32 v8, v5, v8
	v_mul_f32_e32 v4, v5, v4
	v_lshlrev_b32_e32 v5, 16, v40
	v_sub_f32_e32 v5, v5, v6
	v_and_b32_e32 v9, 0xffff0000, v40
	v_mul_f32_e32 v5, v7, v5
	v_sub_f32_e32 v6, v9, v6
	v_fma_f32 v4, v1, v4, v3
	v_fma_f32 v5, v0, v5, v2
	v_mul_f32_e32 v6, v7, v6
	v_fma_f32 v8, v0, v8, v2
	v_fma_f32 v6, v1, v6, v3
	v_cvt_pk_bf16_f32 v5, v8, v5
	ds_write_b32 v222, v5 offset:1024
	v_cvt_pk_bf16_f32 v4, v4, v6
	ds_write_b32 v222, v4 offset:1296
	ds_read_b128 v[4:7], v223
	v_lshlrev_b32_e32 v8, 16, v41
	v_and_b32_e32 v9, 0xffff0000, v41
	v_lshl_add_u64 v[40:41], s[24:25], 0, v[18:19]
	v_lshl_add_u64 v[18:19], v[18:19], 0, s[12:13]
	s_waitcnt lgkmcnt(0)
; #define LAS __attribute__((address_space(3)))
; __device__ __forceinline__ void post_phase(const Args& a, int li, LAS unsigned char* lds) {
;     ...
;               for (int it = 0; it < 8; ++it) { const int tt = tp + 8 * it; const unsigned wa = wa_[it], wb = wb_[it];
;                   const f32x2 sa = *(const LAS f32x2*)(lds + PZ_STAT + (2 * tt) * 8), sb = *(const LAS f32x2*)(lds + PZ_STAT + (2 * tt + 1) * 8);
;                   const float za0 = (bflo(wa) - sa.x) * sa.y * g0 + b0, za1 = (bfhi(wa) - sa.x) * sa.y * g1 + b1, zb0 = (bflo(wb) - sb.x) * sb.y * g0 + b0, zb1 = (bfhi(wb) - sb.x) * sb.y * g1 + b1;
;                   *(LAS unsigned*)(lds + PZ_ZT + (2 * cp) * 272 + (2 * tt) * 2) = pk2(za0, zb0); *(LAS unsigned*)(lds + PZ_ZT + (2 * cp + 1) * 272 + (2 * tt) * 2) = pk2(za1, zb1); } }
;             { const int i = tid >> 2, seg = tid & 3; const bf16* src = spw + (size_t)(g * 128 + i) * 128 + 32 * seg;
; #pragma unroll
;               for (int v = 0; v < 4; ++v) *(LAS u32x4*)(lds + PZ_WM + i * 272 + (32 * seg + 8 * v) * 2) = *(const u32x4*)(src + 8 * v); }
;             __syncthreads();
;             { const int db = wave; bf16x8 Af[4];
; #pragma unroll
;               for (int kk = 0; kk < 4; ++kk) Af[kk] = *(const LAS bf16x8*)(lds + PZ_ZT + (16 * db + n16) * 272 + (32 * kk + 8 * q4) * 2);
;               u32x2 uws[8]; float biases[8];
; #pragma unroll
;               for (int ib = 0; ib < 8; ++ib) { const int i = 16 * ib + n16; uws[ib] = *(const u32x2*)(proj + (t0 + i) * P_EVEN + 1792 + 128 * g + 16 * db + 4 * q4); biases[ib] = sp_b[g * 128 + i]; }
; #pragma unroll
;               for (int ib = 0; ib < 8; ++ib) { f32x4 acc = {0.f, 0.f, 0.f, 0.f};
; #pragma unroll
;                   for (int kk = 0; kk < 4; ++kk) if (32 * kk <= 16 * ib + 15) { const bf16x8 Bf = *(const LAS bf16x8*)(lds + PZ_WM + (16 * ib + n16) * 272 + (32 * kk + 8 * q4) * 2);
;                       acc = __builtin_amdgcn_mfma_f32_16x16x32_bf16(Af[kk], Bf, acc, 0, 0, 0); }
;                   const int i = 16 * ib + n16, c = 128 * g + 16 * db + 4 * q4; const float bias = biases[ib];
;                   const u32x2 uw = uws[ib];
;                   u32x2 o; o.x = pk2(bflo(uw.x) * (acc[0] + bias), bfhi(uw.x) * (acc[1] + bias)); o.y = pk2(bflo(uw.y) * (acc[2] + bias), bfhi(uw.y) * (acc[3] + bias));
;                   *(u32x2*)(ycat + (t0 + i) * DM + 512 + c) = o; } }
	v_sub_f32_e32 v8, v8, v4
	v_sub_f32_e32 v4, v9, v4
	v_mul_f32_e32 v8, v5, v8
	v_mul_f32_e32 v4, v5, v4
	v_lshlrev_b32_e32 v5, 16, v42
	v_sub_f32_e32 v5, v5, v6
	v_and_b32_e32 v9, 0xffff0000, v42
	v_mul_f32_e32 v5, v7, v5
	v_sub_f32_e32 v6, v9, v6
	v_fma_f32 v4, v1, v4, v3
	v_fma_f32 v5, v0, v5, v2
	v_mul_f32_e32 v6, v7, v6
	v_fma_f32 v8, v0, v8, v2
	v_fma_f32 v6, v1, v6, v3
	v_cvt_pk_bf16_f32 v5, v8, v5
	ds_write_b32 v224, v5 offset:1024
	v_cvt_pk_bf16_f32 v4, v4, v6
	ds_write_b32 v224, v4 offset:1296
	ds_read_b128 v[4:7], v225
	v_lshlrev_b32_e32 v8, 16, v43
	v_and_b32_e32 v9, 0xffff0000, v43
	s_waitcnt lgkmcnt(0)
	v_sub_f32_e32 v8, v8, v4
	v_sub_f32_e32 v4, v9, v4
	v_mul_f32_e32 v8, v5, v8
	v_mul_f32_e32 v4, v5, v4
	v_lshlrev_b32_e32 v5, 16, v44
	v_sub_f32_e32 v5, v5, v6
	v_and_b32_e32 v9, 0xffff0000, v44
	v_mul_f32_e32 v5, v7, v5
	v_sub_f32_e32 v6, v9, v6
	v_fma_f32 v4, v1, v4, v3
	v_fma_f32 v5, v0, v5, v2
	v_mul_f32_e32 v6, v7, v6
	v_fma_f32 v8, v0, v8, v2
	v_fma_f32 v6, v1, v6, v3
	v_cvt_pk_bf16_f32 v5, v8, v5
	ds_write_b32 v234, v5 offset:1024
	v_cvt_pk_bf16_f32 v4, v4, v6
	ds_write_b32 v234, v4 offset:1296
	ds_read_b128 v[4:7], v235
	v_lshlrev_b32_e32 v8, 16, v45
	v_and_b32_e32 v9, 0xffff0000, v45
	v_lshl_add_u64 v[44:45], v[130:131], 0, s[26:27]
	s_add_u32 s26, s26, 0x200
	s_waitcnt lgkmcnt(0)
	v_sub_f32_e32 v8, v8, v4
	v_sub_f32_e32 v4, v9, v4
	v_mul_f32_e32 v8, v5, v8
	v_mul_f32_e32 v4, v5, v4
	v_lshlrev_b32_e32 v5, 16, v46
	v_sub_f32_e32 v5, v5, v6
	v_mul_f32_e32 v5, v7, v5
	v_fma_f32 v8, v0, v8, v2
	v_fma_f32 v0, v0, v5, v2
	v_and_b32_e32 v2, 0xffff0000, v46
	v_sub_f32_e32 v2, v2, v6
	v_mul_f32_e32 v2, v7, v2
	v_cvt_pk_bf16_f32 v0, v8, v0
	v_fma_f32 v4, v1, v4, v3
	v_fmac_f32_e32 v3, v1, v2
	ds_write_b32 v236, v0 offset:1024
	v_cvt_pk_bf16_f32 v0, v4, v3
	ds_write_b32 v236, v0 offset:1296
	v_lshl_add_u64 v[0:1], s[24:25], 0, v[38:39]
	v_add_co_u32_e32 v4, vcc, s2, v0
	s_mov_b32 s2, 0xe000000
	s_nop 0
	v_addc_co_u32_e32 v5, vcc, 0, v1, vcc
	flat_load_dwordx4 v[0:3], v[4:5]
	flat_load_dwordx4 v[8:11], v[4:5] offset:16
	flat_load_dwordx4 v[12:15], v[4:5] offset:32
	flat_load_dwordx4 v[52:55], v[4:5] offset:48
	v_add_co_u32_e32 v42, vcc, s2, v40
	s_mov_b32 s2, 0xe016000
	s_nop 0
	v_addc_co_u32_e32 v43, vcc, 0, v41, vcc
	s_addc_u32 s27, s27, 0
	v_lshl_add_u64 v[38:39], v[38:39], 0, s[28:29]
	s_cmpk_eq_i32 s26, 0x800
	s_waitcnt vmcnt(0) lgkmcnt(0)
	ds_write_b128 v237, v[0:3] offset:35840
	ds_write_b128 v237, v[8:11] offset:35856
	ds_write_b128 v237, v[12:15] offset:35872
	ds_write_b128 v237, v[52:55] offset:35888
	s_waitcnt lgkmcnt(0)
	s_barrier
	ds_read_b128 v[12:15], v238 offset:1024
	ds_read_b128 v[8:11], v238 offset:1088
	ds_read_b128 v[4:7], v238 offset:1152
	ds_read_b128 v[0:3], v238 offset:1216
	flat_load_dwordx2 v[48:49], v[42:43] offset:3584
	global_load_dword v60, v[44:45], off
	v_add_co_u32_e32 v42, vcc, s2, v40
	s_mov_b32 s2, 0xe02c000
	s_nop 0
	v_addc_co_u32_e32 v43, vcc, 0, v41, vcc
	flat_load_dwordx2 v[50:51], v[42:43] offset:3584
	global_load_dword v62, v[44:45], off offset:64
	v_add_co_u32_e32 v42, vcc, s2, v40
	s_mov_b32 s2, 0xe042000
	s_nop 0
	v_addc_co_u32_e32 v43, vcc, 0, v41, vcc
	flat_load_dwordx2 v[52:53], v[42:43] offset:3584
	global_load_dword v63, v[44:45], off offset:128
	v_add_co_u32_e32 v42, vcc, s2, v40
	s_mov_b32 s2, 0xe058000
	s_nop 0
	v_addc_co_u32_e32 v43, vcc, 0, v41, vcc
	flat_load_dwordx2 v[54:55], v[42:43] offset:3584
	global_load_dword v64, v[44:45], off offset:192
	v_add_co_u32_e32 v42, vcc, s2, v40
	s_mov_b32 s2, 0xe06e000
	s_nop 0
	v_addc_co_u32_e32 v43, vcc, 0, v41, vcc
	flat_load_dwordx2 v[56:57], v[42:43] offset:3584
	global_load_dword v65, v[44:45], off offset:256
	v_add_co_u32_e32 v42, vcc, s2, v40
	s_mov_b32 s2, 0xe084000
	s_nop 0
	v_addc_co_u32_e32 v43, vcc, 0, v41, vcc
	flat_load_dwordx2 v[58:59], v[42:43] offset:3584
	global_load_dword v66, v[44:45], off offset:320
	v_add_co_u32_e32 v42, vcc, s2, v40
	s_mov_b32 s2, 0xe09a000
	s_nop 0
	v_addc_co_u32_e32 v43, vcc, 0, v41, vcc
	v_add_co_u32_e32 v40, vcc, s2, v40
	flat_load_dwordx2 v[42:43], v[42:43] offset:3584
	s_nop 0
	global_load_dword v67, v[44:45], off offset:384
	v_addc_co_u32_e32 v41, vcc, 0, v41, vcc
	flat_load_dwordx2 v[40:41], v[40:41] offset:3584
	s_nop 0
	global_load_dword v68, v[44:45], off offset:448
	ds_read_b128 v[44:47], v69 offset:35840
	s_waitcnt lgkmcnt(0)
	v_mfma_f32_16x16x32_bf16 v[44:47], v[12:15], v[44:47], 0
	s_waitcnt vmcnt(0)
	v_lshlrev_b32_e32 v61, 16, v48
	s_nop 5
	v_add_f32_e32 v44, v60, v44
	v_and_b32_e32 v48, 0xffff0000, v48
	v_add_f32_e32 v45, v60, v45
	v_mul_f32_e32 v44, v44, v61
	v_mul_f32_e32 v45, v45, v48
	v_cvt_pk_bf16_f32 v44, v44, v45
	v_lshlrev_b32_e32 v45, 16, v49
	v_add_f32_e32 v46, v60, v46
	v_mul_f32_e32 v45, v46, v45
	v_and_b32_e32 v46, 0xffff0000, v49
	v_add_f32_e32 v47, v60, v47
	v_mul_f32_e32 v46, v47, v46
	v_lshlrev_b64 v[60:61], 1, v[36:37]
	v_cvt_pk_bf16_f32 v45, v45, v46
	v_lshl_add_u64 v[46:47], v[20:21], 0, v[60:61]
	flat_store_dwordx2 v[46:47], v[44:45] offset:1024
	ds_read_b128 v[44:47], v69 offset:40192
	s_waitcnt lgkmcnt(0)
	v_mfma_f32_16x16x32_bf16 v[44:47], v[12:15], v[44:47], 0
	v_lshlrev_b32_e32 v37, 16, v50
	v_add_u32_e32 v36, 0x80, v36
	s_nop 5
	v_add_f32_e32 v44, v62, v44
	v_mul_f32_e32 v37, v44, v37
	v_and_b32_e32 v44, 0xffff0000, v50
	v_add_f32_e32 v45, v62, v45
	v_mul_f32_e32 v44, v45, v44
	v_cvt_pk_bf16_f32 v44, v37, v44
	v_lshlrev_b32_e32 v37, 16, v51
	v_add_f32_e32 v45, v62, v46
	v_mul_f32_e32 v37, v45, v37
	v_and_b32_e32 v45, 0xffff0000, v51
	v_add_f32_e32 v46, v62, v47
	v_mul_f32_e32 v45, v46, v45
	v_lshl_add_u64 v[46:47], v[22:23], 0, v[60:61]
	v_cvt_pk_bf16_f32 v45, v37, v45
	flat_store_dwordx2 v[46:47], v[44:45] offset:1024
	ds_read_b128 v[44:47], v69 offset:44544
	ds_read_b128 v[48:51], v69 offset:44608
	s_waitcnt lgkmcnt(0)
; #define LAS __attribute__((address_space(3)))
; __device__ __forceinline__ unsigned pk2(float lo, float hi) { unsigned r; asm volatile("v_cvt_pk_bf16_f32 %0, %1, %2" : "=v"(r) : "v"(lo), "v"(hi)); return r; }
; __device__ __forceinline__ void post_phase(const Args& a, int li, LAS unsigned char* lds) {
;     ...
;               for (int ib = 0; ib < 8; ++ib) { f32x4 acc = {0.f, 0.f, 0.f, 0.f};
; #pragma unroll
;                   for (int kk = 0; kk < 4; ++kk) if (32 * kk <= 16 * ib + 15) { const bf16x8 Bf = *(const LAS bf16x8*)(lds + PZ_WM + (16 * ib + n16) * 272 + (32 * kk + 8 * q4) * 2);
;                       acc = __builtin_amdgcn_mfma_f32_16x16x32_bf16(Af[kk], Bf, acc, 0, 0, 0); }
;                   const int i = 16 * ib + n16, c = 128 * g + 16 * db + 4 * q4; const float bias = biases[ib];
;                   const u32x2 uw = uws[ib];
;                   u32x2 o; o.x = pk2(bflo(uw.x) * (acc[0] + bias), bfhi(uw.x) * (acc[1] + bias)); o.y = pk2(bflo(uw.y) * (acc[2] + bias), bfhi(uw.y) * (acc[3] + bias));
;                   *(u32x2*)(ycat + (t0 + i) * DM + 512 + c) = o; } }
;             __syncthreads();
;         }
;         { const int h = wave; bf16x8 Ag[4][4];
; #pragma unroll
;           for (int cb = 0; cb < 4; ++cb)
; #pragma unroll
;               for (int kk = 0; kk < 4; ++kk) Ag[cb][kk] = *(const bf16x8*)(gupt + (size_t)(64 * h + 16 * cb + n16) * 128 + 32 * kk + 8 * q4);
	v_mfma_f32_16x16x32_bf16 v[44:47], v[12:15], v[44:47], 0
	v_lshlrev_b32_e32 v37, 16, v52
	v_mfma_f32_16x16x32_bf16 v[44:47], v[8:11], v[48:51], v[44:47]
	s_nop 7
	v_add_f32_e32 v44, v63, v44
	v_mul_f32_e32 v37, v44, v37
	v_and_b32_e32 v44, 0xffff0000, v52
	v_add_f32_e32 v45, v63, v45
	v_mul_f32_e32 v44, v45, v44
	v_cvt_pk_bf16_f32 v44, v37, v44
	v_lshlrev_b32_e32 v37, 16, v53
	v_add_f32_e32 v45, v63, v46
	v_mul_f32_e32 v37, v45, v37
	v_and_b32_e32 v45, 0xffff0000, v53
	v_add_f32_e32 v46, v63, v47
	v_mul_f32_e32 v45, v46, v45
	v_lshl_add_u64 v[46:47], v[24:25], 0, v[60:61]
	v_cvt_pk_bf16_f32 v45, v37, v45
	flat_store_dwordx2 v[46:47], v[44:45] offset:1024
	ds_read_b128 v[44:47], v69 offset:48896
	ds_read_b128 v[48:51], v69 offset:48960
	s_waitcnt lgkmcnt(0)
	v_mfma_f32_16x16x32_bf16 v[44:47], v[12:15], v[44:47], 0
	v_lshlrev_b32_e32 v37, 16, v54
	v_mfma_f32_16x16x32_bf16 v[44:47], v[8:11], v[48:51], v[44:47]
	s_nop 7
	v_add_f32_e32 v44, v64, v44
	v_mul_f32_e32 v37, v44, v37
	v_and_b32_e32 v44, 0xffff0000, v54
	v_add_f32_e32 v45, v64, v45
	v_mul_f32_e32 v44, v45, v44
	v_cvt_pk_bf16_f32 v44, v37, v44
	v_lshlrev_b32_e32 v37, 16, v55
	v_add_f32_e32 v45, v64, v46
	v_mul_f32_e32 v37, v45, v37
	v_and_b32_e32 v45, 0xffff0000, v55
	v_add_f32_e32 v46, v64, v47
	v_mul_f32_e32 v45, v46, v45
	v_lshl_add_u64 v[46:47], v[26:27], 0, v[60:61]
	v_cvt_pk_bf16_f32 v45, v37, v45
	flat_store_dwordx2 v[46:47], v[44:45] offset:1024
	ds_read_b128 v[44:47], v69 offset:53248
	ds_read_b128 v[48:51], v69 offset:53312
	s_waitcnt lgkmcnt(0)
	v_mfma_f32_16x16x32_bf16 v[44:47], v[12:15], v[44:47], 0
	v_lshlrev_b32_e32 v37, 16, v56
	v_mfma_f32_16x16x32_bf16 v[44:47], v[8:11], v[48:51], v[44:47]
	ds_read_b128 v[48:51], v69 offset:53376
	s_waitcnt lgkmcnt(0)
	v_mfma_f32_16x16x32_bf16 v[44:47], v[4:7], v[48:51], v[44:47]
	s_nop 7
	v_add_f32_e32 v44, v65, v44
	v_mul_f32_e32 v37, v44, v37
	v_and_b32_e32 v44, 0xffff0000, v56
	v_add_f32_e32 v45, v65, v45
	v_mul_f32_e32 v44, v45, v44
	v_cvt_pk_bf16_f32 v44, v37, v44
	v_lshlrev_b32_e32 v37, 16, v57
	v_add_f32_e32 v45, v65, v46
	v_mul_f32_e32 v37, v45, v37
	v_and_b32_e32 v45, 0xffff0000, v57
	v_add_f32_e32 v46, v65, v47
	v_mul_f32_e32 v45, v46, v45
	v_lshl_add_u64 v[46:47], v[28:29], 0, v[60:61]
	v_cvt_pk_bf16_f32 v45, v37, v45
	flat_store_dwordx2 v[46:47], v[44:45] offset:1024
	ds_read_b128 v[44:47], v69 offset:57600
	ds_read_b128 v[48:51], v69 offset:57664
	s_waitcnt lgkmcnt(0)
	v_mfma_f32_16x16x32_bf16 v[44:47], v[12:15], v[44:47], 0
	v_lshlrev_b32_e32 v37, 16, v58
	v_mfma_f32_16x16x32_bf16 v[44:47], v[8:11], v[48:51], v[44:47]
	ds_read_b128 v[48:51], v69 offset:57728
	s_waitcnt lgkmcnt(0)
	v_mfma_f32_16x16x32_bf16 v[44:47], v[4:7], v[48:51], v[44:47]
	s_nop 7
	v_add_f32_e32 v44, v66, v44
	v_mul_f32_e32 v37, v44, v37
	v_and_b32_e32 v44, 0xffff0000, v58
	v_add_f32_e32 v45, v66, v45
	v_mul_f32_e32 v44, v45, v44
	v_cvt_pk_bf16_f32 v44, v37, v44
	v_lshlrev_b32_e32 v37, 16, v59
	v_add_f32_e32 v45, v66, v46
	v_mul_f32_e32 v37, v45, v37
	v_and_b32_e32 v45, 0xffff0000, v59
	v_add_f32_e32 v46, v66, v47
	v_mul_f32_e32 v45, v46, v45
	v_lshl_add_u64 v[46:47], v[30:31], 0, v[60:61]
	v_cvt_pk_bf16_f32 v45, v37, v45
	flat_store_dwordx2 v[46:47], v[44:45] offset:1024
	ds_read_b128 v[44:47], v69 offset:61952
	ds_read_b128 v[48:51], v69 offset:62016
	s_waitcnt lgkmcnt(0)
	v_mfma_f32_16x16x32_bf16 v[44:47], v[12:15], v[44:47], 0
	v_lshlrev_b32_e32 v37, 16, v42
	v_and_b32_e32 v42, 0xffff0000, v42
	v_mfma_f32_16x16x32_bf16 v[44:47], v[8:11], v[48:51], v[44:47]
	ds_read_b128 v[48:51], v69 offset:62080
	s_waitcnt lgkmcnt(0)
	v_mfma_f32_16x16x32_bf16 v[44:47], v[4:7], v[48:51], v[44:47]
	ds_read_b128 v[48:51], v69 offset:62144
	s_waitcnt lgkmcnt(0)
	v_mfma_f32_16x16x32_bf16 v[44:47], v[0:3], v[48:51], v[44:47]
	s_nop 7
	v_add_f32_e32 v44, v67, v44
	v_mul_f32_e32 v37, v44, v37
	v_add_f32_e32 v44, v67, v45
	v_mul_f32_e32 v42, v44, v42
	v_cvt_pk_bf16_f32 v42, v37, v42
	v_lshlrev_b32_e32 v37, 16, v43
	v_add_f32_e32 v44, v67, v46
	v_mul_f32_e32 v37, v44, v37
	v_and_b32_e32 v43, 0xffff0000, v43
	v_add_f32_e32 v44, v67, v47
	v_mul_f32_e32 v43, v44, v43
	v_lshl_add_u64 v[44:45], v[32:33], 0, v[60:61]
	v_cvt_pk_bf16_f32 v43, v37, v43
	flat_store_dwordx2 v[44:45], v[42:43] offset:1024
	ds_read_b128 v[42:45], v239 offset:61952
	s_waitcnt lgkmcnt(0)
	v_mfma_f32_16x16x32_bf16 v[12:15], v[12:15], v[42:45], 0
	ds_read_b128 v[42:45], v239 offset:62016
	s_waitcnt lgkmcnt(0)
	v_mfma_f32_16x16x32_bf16 v[8:11], v[8:11], v[42:45], v[12:15]
	s_nop 4
	ds_read_b128 v[12:15], v239 offset:62080
	s_waitcnt lgkmcnt(0)
	v_mfma_f32_16x16x32_bf16 v[4:7], v[4:7], v[12:15], v[8:11]
	s_nop 2
	ds_read_b128 v[8:11], v239 offset:62144
	s_waitcnt lgkmcnt(0)
	v_mfma_f32_16x16x32_bf16 v[0:3], v[0:3], v[8:11], v[4:7]
	s_nop 2
	v_lshlrev_b32_e32 v4, 16, v40
	s_nop 3
	v_add_f32_e32 v0, v68, v0
	v_mul_f32_e32 v0, v0, v4
	v_and_b32_e32 v4, 0xffff0000, v40
	v_add_f32_e32 v1, v68, v1
	v_mul_f32_e32 v1, v1, v4
	v_cvt_pk_bf16_f32 v0, v0, v1
	v_lshlrev_b32_e32 v1, 16, v41
	v_add_f32_e32 v2, v68, v2
	v_mul_f32_e32 v1, v2, v1
	v_and_b32_e32 v2, 0xffff0000, v41
	v_add_f32_e32 v3, v68, v3
	v_mul_f32_e32 v2, v3, v2
	v_cvt_pk_bf16_f32 v1, v1, v2
	v_lshl_add_u64 v[2:3], v[34:35], 0, v[60:61]
	flat_store_dwordx2 v[2:3], v[0:1] offset:1024
	s_waitcnt lgkmcnt(0)
	s_barrier
	s_cbranch_scc0 .LBB0_655
	flat_load_dwordx4 v[0:3], v[100:101]
	flat_load_dwordx4 v[4:7], v[100:101] offset:64
	flat_load_dwordx4 v[8:11], v[100:101] offset:128
	flat_load_dwordx4 v[12:15], v[100:101] offset:192
	flat_load_dwordx4 v[16:19], v[102:103]
	flat_load_dwordx4 v[20:23], v[102:103] offset:64
	flat_load_dwordx4 v[24:27], v[102:103] offset:128
	flat_load_dwordx4 v[28:31], v[102:103] offset:192
	flat_load_dwordx4 v[32:35], v[104:105]
	flat_load_dwordx4 v[36:39], v[104:105] offset:64
	flat_load_dwordx4 v[40:43], v[104:105] offset:128
	flat_load_dwordx4 v[44:47], v[104:105] offset:192
	flat_load_dwordx4 v[48:51], v[106:107]
	flat_load_dwordx4 v[52:55], v[106:107] offset:64
	flat_load_dwordx4 v[56:59], v[106:107] offset:128
	flat_load_dwordx4 v[60:63], v[106:107] offset:192
	s_bfe_u32 s2, s7, 0x50007
	v_lshl_add_u64 v[150:151], v[136:137], 0, s[0:1]
	v_lshl_add_u64 v[152:153], v[138:139], 0, s[0:1]
	v_lshl_add_u64 v[154:155], v[140:141], 0, s[0:1]
	v_lshl_add_u64 v[156:157], v[142:143], 0, s[0:1]
	s_lshl_b64 s[0:1], s[46:47], 12
	s_mul_i32 s4, s2, 0x8800
	s_lshl_b64 s[2:3], s[46:47], 18
	v_lshl_add_u64 v[158:159], v[144:145], 0, s[0:1]
	s_lshl_b64 s[0:1], s[46:47], 17
	v_lshl_add_u64 v[148:149], v[134:135], 0, s[2:3]
	v_lshl_add_u64 v[160:161], v[146:147], 0, s[0:1]
	v_add_u32_e32 v241, s4, v93
	s_mov_b32 s2, 0
	s_branch .LBB0_658

;     __device__ __forceinline__ void operator()(f32x4 (&acc)[2][2][4][2], const Unit& u, int wr, int wc, int fr_, int fq_) const {
;     ...
;                 for (int m = 0; m < 4; ++m)
; #pragma unroll
;                     for (int bj = 0; bj < 2; ++bj) { const u32x4 q = bsh[m][bj];
;                         acc[ai][bj][m][0] += (f32x4){__builtin_bit_cast(float, q.x << 16), __builtin_bit_cast(float, q.x & 0xffff0000u), __builtin_bit_cast(float, q.y << 16), __builtin_bit_cast(float, q.y & 0xffff0000u)};
;                         acc[ai][bj][m][1] += (f32x4){__builtin_bit_cast(float, q.z << 16), __builtin_bit_cast(float, q.z & 0xffff0000u), __builtin_bit_cast(float, q.w << 16), __builtin_bit_cast(float, q.w & 0xffff0000u)}; }
;                 asm volatile("" ::: "memory"); }
;         }
; #pragma unroll
;         for (int ai = 0; ai < 2; ++ai)
; #pragma unroll
;             for (int m = 0; m < 4; ++m) { float ss = 0.f;
; #pragma unroll
;                 for (int bj = 0; bj < 2; ++bj) { const f32x4 h0 = acc[ai][bj][m][0], h1 = acc[ai][bj][m][1];
;                     ss += ((h0[0] * h0[0] + h0[1] * h0[1]) + (h0[2] * h0[2] + h0[3] * h0[3])) + ((h1[0] * h1[0] + h1[1] * h1[1]) + (h1[2] * h1[2] + h1[3] * h1[3])); }
;                 ss += __builtin_bit_cast(float, __builtin_amdgcn_ds_bpermute((lane ^ 16) << 2, __builtin_bit_cast(int, ss)));
;                 ss += __builtin_bit_cast(float, __builtin_amdgcn_ds_bpermute((lane ^ 32) << 2, __builtin_bit_cast(int, ss)));
;                 if (fq == 0) P[(ai * HALF + wr * 64 + m * 16 + fr) * 4 + wc] = ss; }
.LBB0_738:
	s_or_b64 exec, exec, s[6:7]
	v_lshlrev_b32_e32 v170, 16, v164
	v_and_b32_e32 v171, 0xffff0000, v164
	v_pk_add_f32 v[216:217], v[108:109], v[170:171]
	v_lshlrev_b32_e32 v108, 16, v166
	v_and_b32_e32 v109, 0xffff0000, v166
	v_lshlrev_b32_e32 v164, 16, v165
	v_and_b32_e32 v165, 0xffff0000, v165
	v_pk_add_f32 v[220:221], v[104:105], v[108:109]
	v_lshlrev_b32_e32 v104, 16, v160
	v_and_b32_e32 v105, 0xffff0000, v160
	s_waitcnt lgkmcnt(0)
	v_pk_add_f32 v[214:215], v[110:111], v[164:165]
	v_lshlrev_b32_e32 v110, 16, v167
	v_and_b32_e32 v111, 0xffff0000, v167
	v_pk_add_f32 v[164:165], v[100:101], v[104:105]
	v_lshlrev_b32_e32 v100, 16, v162
	v_and_b32_e32 v101, 0xffff0000, v162
	v_pk_add_f32 v[218:219], v[106:107], v[110:111]
	v_lshlrev_b32_e32 v106, 16, v161
	v_and_b32_e32 v107, 0xffff0000, v161
	v_pk_add_f32 v[166:167], v[96:97], v[100:101]
	v_mul_f32_e32 v96, v217, v217
	v_mul_f32_e32 v97, v215, v215
	v_pk_add_f32 v[160:161], v[102:103], v[106:107]
	v_lshlrev_b32_e32 v102, 16, v163
	v_and_b32_e32 v103, 0xffff0000, v163
	v_fmac_f32_e32 v96, v216, v216
	v_fmac_f32_e32 v97, v214, v214
	v_pk_add_f32 v[162:163], v[98:99], v[102:103]
	v_add_f32_e32 v96, v96, v97
	v_mul_f32_e32 v97, v221, v221
	v_mul_f32_e32 v98, v219, v219
	v_fmac_f32_e32 v97, v220, v220
	v_fmac_f32_e32 v98, v218, v218
	v_add_f32_e32 v97, v97, v98
	v_add_f32_e32 v96, v96, v97
	v_mul_f32_e32 v97, v165, v165
	v_mul_f32_e32 v98, v161, v161
	v_fmac_f32_e32 v97, v164, v164
	v_fmac_f32_e32 v98, v160, v160
	v_add_f32_e32 v97, v97, v98
	v_mul_f32_e32 v98, v167, v167
	v_mul_f32_e32 v99, v163, v163
	v_fmac_f32_e32 v98, v166, v166
	v_fmac_f32_e32 v99, v162, v162
	v_add_f32_e32 v98, v98, v99
	v_add_f32_e32 v97, v97, v98
	v_add_f32_e32 v173, v96, v97
	v_lshlrev_b32_e32 v96, 16, v152
	s_waitcnt lgkmcnt(0)
	v_and_b32_e32 v97, 0xffff0000, v152
	v_pk_add_f32 v[110:111], v[92:93], v[96:97]
	v_lshlrev_b32_e32 v92, 16, v154
	v_and_b32_e32 v93, 0xffff0000, v154
	v_lshlrev_b32_e32 v98, 16, v153
	v_and_b32_e32 v99, 0xffff0000, v153
	v_pk_add_f32 v[106:107], v[88:89], v[92:93]
	v_lshlrev_b32_e32 v88, 16, v144
	v_and_b32_e32 v89, 0xffff0000, v144
	v_pk_add_f32 v[108:109], v[94:95], v[98:99]
	v_lshlrev_b32_e32 v94, 16, v155
	v_and_b32_e32 v95, 0xffff0000, v155
	v_pk_add_f32 v[84:85], v[84:85], v[88:89]
	v_lshlrev_b32_e32 v88, 16, v146
	v_and_b32_e32 v89, 0xffff0000, v146
	v_pk_add_f32 v[102:103], v[90:91], v[94:95]
	v_lshlrev_b32_e32 v90, 16, v145
	v_and_b32_e32 v91, 0xffff0000, v145
	v_pk_add_f32 v[80:81], v[80:81], v[88:89]
	v_mul_f32_e32 v88, v111, v111
	v_mul_f32_e32 v89, v109, v109
	v_pk_add_f32 v[86:87], v[86:87], v[90:91]
	v_lshlrev_b32_e32 v90, 16, v147
	v_and_b32_e32 v91, 0xffff0000, v147
	v_fmac_f32_e32 v88, v110, v110
	v_fmac_f32_e32 v89, v108, v108
	v_pk_add_f32 v[82:83], v[82:83], v[90:91]
	v_add_f32_e32 v88, v88, v89
	v_mul_f32_e32 v89, v107, v107
	v_mul_f32_e32 v90, v103, v103
	v_fmac_f32_e32 v89, v106, v106
	v_fmac_f32_e32 v90, v102, v102
	v_add_f32_e32 v89, v89, v90
	v_add_f32_e32 v88, v88, v89
	v_mul_f32_e32 v89, v85, v85
	v_mul_f32_e32 v90, v87, v87
	v_fmac_f32_e32 v89, v84, v84
	v_fmac_f32_e32 v90, v86, v86
	v_add_f32_e32 v89, v89, v90
	v_mul_f32_e32 v90, v81, v81
	v_mul_f32_e32 v91, v83, v83
	v_fmac_f32_e32 v90, v80, v80
	v_fmac_f32_e32 v91, v82, v82
	v_add_f32_e32 v90, v90, v91
	v_add_f32_e32 v89, v89, v90
	v_add_f32_e32 v178, v88, v89
	v_lshlrev_b32_e32 v88, 16, v136
	s_waitcnt lgkmcnt(0)
	v_and_b32_e32 v89, 0xffff0000, v136
	v_pk_add_f32 v[100:101], v[76:77], v[88:89]
	v_lshlrev_b32_e32 v76, 16, v138
	v_and_b32_e32 v77, 0xffff0000, v138
	v_lshlrev_b32_e32 v90, 16, v137
	v_and_b32_e32 v91, 0xffff0000, v137
	v_pk_add_f32 v[104:105], v[72:73], v[76:77]
	v_lshlrev_b32_e32 v72, 16, v128
	v_and_b32_e32 v73, 0xffff0000, v128
	v_pk_add_f32 v[90:91], v[78:79], v[90:91]
	v_lshlrev_b32_e32 v78, 16, v139
	v_and_b32_e32 v79, 0xffff0000, v139
	v_pk_add_f32 v[68:69], v[68:69], v[72:73]
	v_lshlrev_b32_e32 v72, 16, v130
	v_and_b32_e32 v73, 0xffff0000, v130
	v_pk_add_f32 v[96:97], v[74:75], v[78:79]
	v_lshlrev_b32_e32 v74, 16, v129
	v_and_b32_e32 v75, 0xffff0000, v129
	v_pk_add_f32 v[64:65], v[64:65], v[72:73]
	v_mul_f32_e32 v72, v101, v101
	v_mul_f32_e32 v73, v91, v91
	v_pk_add_f32 v[70:71], v[70:71], v[74:75]
	v_lshlrev_b32_e32 v74, 16, v131
	v_and_b32_e32 v75, 0xffff0000, v131
	v_fmac_f32_e32 v72, v100, v100
	v_fmac_f32_e32 v73, v90, v90
	v_pk_add_f32 v[66:67], v[66:67], v[74:75]
	v_add_f32_e32 v72, v72, v73
	v_mul_f32_e32 v73, v105, v105
	v_mul_f32_e32 v74, v97, v97
	v_fmac_f32_e32 v73, v104, v104
	v_fmac_f32_e32 v74, v96, v96
	v_add_f32_e32 v73, v73, v74
	v_add_f32_e32 v72, v72, v73
	v_mul_f32_e32 v73, v69, v69
	v_mul_f32_e32 v74, v71, v71
	v_fmac_f32_e32 v73, v68, v68
	v_fmac_f32_e32 v74, v70, v70
	v_add_f32_e32 v73, v73, v74
	v_mul_f32_e32 v74, v65, v65
	v_mul_f32_e32 v75, v67, v67
	v_fmac_f32_e32 v74, v64, v64
	v_fmac_f32_e32 v75, v66, v66
	v_add_f32_e32 v74, v74, v75
	v_add_f32_e32 v73, v73, v74
	v_add_f32_e32 v179, v72, v73
	s_waitcnt vmcnt(0)
	v_lshlrev_b32_e32 v72, 16, v156
	s_waitcnt lgkmcnt(0)
;     __device__ __forceinline__ void operator()(f32x4 (&acc)[2][2][4][2], const Unit& u, int wr, int wc, int fr_, int fq_) const {
;     ...
;                 for (int m = 0; m < 4; ++m)
; #pragma unroll
;                     for (int bj = 0; bj < 2; ++bj) { const u32x4 q = bsh[m][bj];
;                         acc[ai][bj][m][0] += (f32x4){__builtin_bit_cast(float, q.x << 16), __builtin_bit_cast(float, q.x & 0xffff0000u), __builtin_bit_cast(float, q.y << 16), __builtin_bit_cast(float, q.y & 0xffff0000u)};
;                         acc[ai][bj][m][1] += (f32x4){__builtin_bit_cast(float, q.z << 16), __builtin_bit_cast(float, q.z & 0xffff0000u), __builtin_bit_cast(float, q.w << 16), __builtin_bit_cast(float, q.w & 0xffff0000u)}; }
;                 asm volatile("" ::: "memory"); }
;         }
; #pragma unroll
;         for (int ai = 0; ai < 2; ++ai)
; #pragma unroll
;             for (int m = 0; m < 4; ++m) { float ss = 0.f;
; #pragma unroll
;                 for (int bj = 0; bj < 2; ++bj) { const f32x4 h0 = acc[ai][bj][m][0], h1 = acc[ai][bj][m][1];
;                     ss += ((h0[0] * h0[0] + h0[1] * h0[1]) + (h0[2] * h0[2] + h0[3] * h0[3])) + ((h1[0] * h1[0] + h1[1] * h1[1]) + (h1[2] * h1[2] + h1[3] * h1[3])); }
;                 ss += __builtin_bit_cast(float, __builtin_amdgcn_ds_bpermute((lane ^ 16) << 2, __builtin_bit_cast(int, ss)));
;                 ss += __builtin_bit_cast(float, __builtin_amdgcn_ds_bpermute((lane ^ 32) << 2, __builtin_bit_cast(int, ss)));
;                 if (fq == 0) P[(ai * HALF + wr * 64 + m * 16 + fr) * 4 + wc] = ss; }
	v_and_b32_e32 v73, 0xffff0000, v156
	v_pk_add_f32 v[94:95], v[60:61], v[72:73]
	v_lshlrev_b32_e32 v60, 16, v158
	v_and_b32_e32 v61, 0xffff0000, v158
	v_lshlrev_b32_e32 v74, 16, v157
	v_and_b32_e32 v75, 0xffff0000, v157
	v_pk_add_f32 v[98:99], v[56:57], v[60:61]
	v_lshlrev_b32_e32 v56, 16, v148
	v_and_b32_e32 v57, 0xffff0000, v148
	v_pk_add_f32 v[74:75], v[62:63], v[74:75]
	v_lshlrev_b32_e32 v62, 16, v159
	v_and_b32_e32 v63, 0xffff0000, v159
	v_pk_add_f32 v[52:53], v[52:53], v[56:57]
	v_lshlrev_b32_e32 v56, 16, v150
	v_and_b32_e32 v57, 0xffff0000, v150
	v_pk_add_f32 v[88:89], v[58:59], v[62:63]
	v_lshlrev_b32_e32 v58, 16, v149
	v_and_b32_e32 v59, 0xffff0000, v149
	v_pk_add_f32 v[48:49], v[48:49], v[56:57]
	v_mul_f32_e32 v56, v95, v95
	v_mul_f32_e32 v57, v75, v75
	v_pk_add_f32 v[54:55], v[54:55], v[58:59]
	v_lshlrev_b32_e32 v58, 16, v151
	v_and_b32_e32 v59, 0xffff0000, v151
	v_fmac_f32_e32 v56, v94, v94
	v_fmac_f32_e32 v57, v74, v74
	v_pk_add_f32 v[50:51], v[50:51], v[58:59]
	v_add_f32_e32 v56, v56, v57
	v_mul_f32_e32 v57, v99, v99
	v_mul_f32_e32 v58, v89, v89
	v_fmac_f32_e32 v57, v98, v98
	v_fmac_f32_e32 v58, v88, v88
	v_add_f32_e32 v57, v57, v58
	v_add_f32_e32 v56, v56, v57
	v_mul_f32_e32 v57, v53, v53
	v_mul_f32_e32 v58, v55, v55
	v_fmac_f32_e32 v57, v52, v52
	v_fmac_f32_e32 v58, v54, v54
	v_add_f32_e32 v57, v57, v58
	v_mul_f32_e32 v58, v49, v49
	v_mul_f32_e32 v59, v51, v51
	v_fmac_f32_e32 v58, v48, v48
	v_fmac_f32_e32 v59, v50, v50
	v_add_f32_e32 v58, v58, v59
	v_add_f32_e32 v57, v57, v58
	v_add_f32_e32 v240, v56, v57
	v_lshlrev_b32_e32 v56, 16, v140
	s_waitcnt lgkmcnt(0)
	v_and_b32_e32 v57, 0xffff0000, v140
	v_pk_add_f32 v[78:79], v[44:45], v[56:57]
	v_lshlrev_b32_e32 v44, 16, v142
	v_and_b32_e32 v45, 0xffff0000, v142
	v_lshlrev_b32_e32 v58, 16, v141
	v_and_b32_e32 v59, 0xffff0000, v141
	v_pk_add_f32 v[92:93], v[40:41], v[44:45]
	v_lshlrev_b32_e32 v40, 16, v132
	v_and_b32_e32 v41, 0xffff0000, v132
	v_pk_add_f32 v[58:59], v[46:47], v[58:59]
	v_lshlrev_b32_e32 v46, 16, v143
	v_and_b32_e32 v47, 0xffff0000, v143
	v_pk_add_f32 v[36:37], v[36:37], v[40:41]
	v_lshlrev_b32_e32 v40, 16, v134
	v_and_b32_e32 v41, 0xffff0000, v134
	v_pk_add_f32 v[72:73], v[42:43], v[46:47]
	v_lshlrev_b32_e32 v42, 16, v133
	v_and_b32_e32 v43, 0xffff0000, v133
	v_pk_add_f32 v[32:33], v[32:33], v[40:41]
	v_mul_f32_e32 v40, v79, v79
	v_mul_f32_e32 v41, v59, v59
	v_pk_add_f32 v[38:39], v[38:39], v[42:43]
	v_lshlrev_b32_e32 v42, 16, v135
	v_and_b32_e32 v43, 0xffff0000, v135
	v_fmac_f32_e32 v40, v78, v78
	v_fmac_f32_e32 v41, v58, v58
	v_pk_add_f32 v[34:35], v[34:35], v[42:43]
	v_add_f32_e32 v40, v40, v41
	v_mul_f32_e32 v41, v93, v93
	v_mul_f32_e32 v42, v73, v73
	v_fmac_f32_e32 v41, v92, v92
	v_fmac_f32_e32 v42, v72, v72
	v_add_f32_e32 v41, v41, v42
	v_add_f32_e32 v40, v40, v41
	v_mul_f32_e32 v41, v37, v37
	v_mul_f32_e32 v42, v39, v39
	v_fmac_f32_e32 v41, v36, v36
	v_fmac_f32_e32 v42, v38, v38
	v_add_f32_e32 v41, v41, v42
	v_mul_f32_e32 v42, v33, v33
	v_mul_f32_e32 v43, v35, v35
	v_fmac_f32_e32 v42, v32, v32
	v_fmac_f32_e32 v43, v34, v34
	v_add_f32_e32 v42, v42, v43
	v_add_f32_e32 v41, v41, v42
	v_add_f32_e32 v241, v40, v41
	v_lshlrev_b32_e32 v40, 16, v124
	s_waitcnt lgkmcnt(0)
;     __device__ __forceinline__ void operator()(f32x4 (&acc)[2][2][4][2], const Unit& u, int wr, int wc, int fr_, int fq_) const {
;     ...
;             for (int m = 0; m < 4; ++m) { float ss = 0.f;
; #pragma unroll
;                 for (int bj = 0; bj < 2; ++bj) { const f32x4 h0 = acc[ai][bj][m][0], h1 = acc[ai][bj][m][1];
;                     ss += ((h0[0] * h0[0] + h0[1] * h0[1]) + (h0[2] * h0[2] + h0[3] * h0[3])) + ((h1[0] * h1[0] + h1[1] * h1[1]) + (h1[2] * h1[2] + h1[3] * h1[3])); }
;                 ss += __builtin_bit_cast(float, __builtin_amdgcn_ds_bpermute((lane ^ 16) << 2, __builtin_bit_cast(int, ss)));
;                 ss += __builtin_bit_cast(float, __builtin_amdgcn_ds_bpermute((lane ^ 32) << 2, __builtin_bit_cast(int, ss)));
;                 if (fq == 0) P[(ai * HALF + wr * 64 + m * 16 + fr) * 4 + wc] = ss; }
	v_and_b32_e32 v41, 0xffff0000, v124
	v_pk_add_f32 v[62:63], v[28:29], v[40:41]
	v_lshlrev_b32_e32 v28, 16, v126
	v_and_b32_e32 v29, 0xffff0000, v126
	v_lshlrev_b32_e32 v42, 16, v125
	v_and_b32_e32 v43, 0xffff0000, v125
	v_pk_add_f32 v[76:77], v[24:25], v[28:29]
	v_lshlrev_b32_e32 v24, 16, v116
	v_and_b32_e32 v25, 0xffff0000, v116
	v_pk_add_f32 v[44:45], v[30:31], v[42:43]
	v_lshlrev_b32_e32 v30, 16, v127
	v_and_b32_e32 v31, 0xffff0000, v127
	v_pk_add_f32 v[28:29], v[20:21], v[24:25]
	v_lshlrev_b32_e32 v20, 16, v118
	v_and_b32_e32 v21, 0xffff0000, v118
	v_pk_add_f32 v[56:57], v[26:27], v[30:31]
	v_pk_add_f32 v[30:31], v[16:17], v[20:21]
	v_mul_f32_e32 v16, v63, v63
	v_mul_f32_e32 v17, v45, v45
	v_lshlrev_b32_e32 v24, 16, v119
	v_and_b32_e32 v25, 0xffff0000, v119
	v_fmac_f32_e32 v16, v62, v62
	v_fmac_f32_e32 v17, v44, v44
	v_pk_add_f32 v[24:25], v[18:19], v[24:25]
	v_add_f32_e32 v16, v16, v17
	v_mul_f32_e32 v17, v77, v77
	v_mul_f32_e32 v18, v57, v57
	v_lshlrev_b32_e32 v26, 16, v117
	v_and_b32_e32 v27, 0xffff0000, v117
	v_fmac_f32_e32 v17, v76, v76
	v_fmac_f32_e32 v18, v56, v56
	v_pk_add_f32 v[22:23], v[22:23], v[26:27]
	v_add_f32_e32 v17, v17, v18
	v_add_f32_e32 v16, v16, v17
	v_mul_f32_e32 v17, v29, v29
	v_mul_f32_e32 v18, v23, v23
	v_fmac_f32_e32 v17, v28, v28
	v_fmac_f32_e32 v18, v22, v22
	v_add_f32_e32 v17, v17, v18
	v_mul_f32_e32 v18, v31, v31
	v_mul_f32_e32 v19, v25, v25
	v_fmac_f32_e32 v18, v30, v30
	v_fmac_f32_e32 v19, v24, v24
	v_add_f32_e32 v18, v18, v19
	v_add_f32_e32 v17, v17, v18
	v_add_f32_e32 v242, v16, v17
	v_lshlrev_b32_e32 v16, 16, v120
	s_waitcnt lgkmcnt(0)
	v_and_b32_e32 v17, 0xffff0000, v120
	v_pk_add_f32 v[46:47], v[12:13], v[16:17]
	v_lshlrev_b32_e32 v12, 16, v122
	v_and_b32_e32 v13, 0xffff0000, v122
	v_lshlrev_b32_e32 v18, 16, v121
	v_and_b32_e32 v19, 0xffff0000, v121
	v_pk_add_f32 v[60:61], v[8:9], v[12:13]
	v_lshlrev_b32_e32 v8, 16, v112
	v_and_b32_e32 v9, 0xffff0000, v112
	v_pk_add_f32 v[40:41], v[14:15], v[18:19]
	v_lshlrev_b32_e32 v14, 16, v123
	v_and_b32_e32 v15, 0xffff0000, v123
	v_pk_add_f32 v[20:21], v[4:5], v[8:9]
	v_lshlrev_b32_e32 v4, 16, v114
	v_and_b32_e32 v5, 0xffff0000, v114
	v_pk_add_f32 v[42:43], v[10:11], v[14:15]
	v_lshlrev_b32_e32 v10, 16, v113
	v_and_b32_e32 v11, 0xffff0000, v113
	v_pk_add_f32 v[26:27], v[0:1], v[4:5]
	v_mul_f32_e32 v0, v47, v47
	v_mul_f32_e32 v1, v41, v41
	v_pk_add_f32 v[16:17], v[6:7], v[10:11]
	v_lshlrev_b32_e32 v6, 16, v115
	v_and_b32_e32 v7, 0xffff0000, v115
	v_fmac_f32_e32 v0, v46, v46
	v_fmac_f32_e32 v1, v40, v40
	v_pk_add_f32 v[18:19], v[2:3], v[6:7]
	v_add_f32_e32 v0, v0, v1
	v_mul_f32_e32 v1, v61, v61
	v_mul_f32_e32 v2, v43, v43
	v_fmac_f32_e32 v1, v60, v60
	v_fmac_f32_e32 v2, v42, v42
	v_add_f32_e32 v1, v1, v2
	v_add_f32_e32 v0, v0, v1
	v_mul_f32_e32 v1, v21, v21
	v_mul_f32_e32 v2, v17, v17
	v_fmac_f32_e32 v1, v20, v20
	v_fmac_f32_e32 v2, v16, v16
	v_add_f32_e32 v1, v1, v2
	v_mul_f32_e32 v2, v27, v27
	v_mul_f32_e32 v3, v19, v19
	v_fmac_f32_e32 v2, v26, v26
	v_fmac_f32_e32 v3, v18, v18
	v_add_f32_e32 v2, v2, v3
	v_add_f32_e32 v1, v1, v2
	v_add_f32_e32 v243, v0, v1
	ds_bpermute_b32 v245, v238, v173
	ds_bpermute_b32 v246, v238, v178
	ds_bpermute_b32 v247, v238, v179
	ds_bpermute_b32 v248, v238, v240
	ds_bpermute_b32 v249, v238, v241
	ds_bpermute_b32 v250, v238, v242
	ds_bpermute_b32 v251, v238, v243
	s_waitcnt lgkmcnt(0)
	v_add_f32_e32 v173, v173, v245
	v_add_f32_e32 v178, v178, v246
	v_add_f32_e32 v179, v179, v247
	v_add_f32_e32 v240, v240, v248
	v_add_f32_e32 v241, v241, v249
	v_add_f32_e32 v242, v242, v250
	v_add_f32_e32 v243, v243, v251
	ds_bpermute_b32 v245, v237, v173
	ds_bpermute_b32 v246, v237, v178
	ds_bpermute_b32 v247, v237, v179
	ds_bpermute_b32 v248, v237, v240
	ds_bpermute_b32 v249, v237, v241
	ds_bpermute_b32 v250, v237, v242
	ds_bpermute_b32 v251, v237, v243
	s_and_saveexec_b64 s[6:7], vcc
	s_cbranch_execz .LBB0_752
	s_waitcnt lgkmcnt(0)
	v_add_f32_e32 v173, v173, v245
	v_add_f32_e32 v178, v178, v246
	v_add_f32_e32 v179, v179, v247
	v_add_f32_e32 v240, v240, v248
	v_add_f32_e32 v241, v241, v249
	v_add_f32_e32 v242, v242, v250
	v_add_f32_e32 v243, v243, v251
	ds_write_b32 v239, v173 offset:256
	ds_write_b32 v239, v178 offset:512
	ds_write_b32 v239, v179 offset:768
	ds_write_b32 v239, v240 offset:2048
	ds_write_b32 v239, v241 offset:2304
	ds_write_b32 v239, v242 offset:2560
	ds_write_b32 v239, v243 offset:2816

;     __device__ __forceinline__ void operator()(f32x4 (&acc)[2][2][4][2], const Unit& u, int wr, int wc, int fr_, int fq_) const {
;     ...
;         if (wid < 4) {
;             const unsigned* slot = xbuf + (size_t)(u.pm * BM + tid) * 4; float s = 0.f;
; #pragma unroll
;             for (int q = 0; q < 4; ++q) s += __builtin_bit_cast(float, __hip_atomic_load(slot + q, __ATOMIC_RELAXED, __HIP_MEMORY_SCOPE_AGENT));
;             S[tid] = __builtin_amdgcn_rsqf(s * (1.0f / 1024.0f) + 1e-5f);
;         }
.LBB0_757:
	s_waitcnt vmcnt(0) lgkmcnt(0)
	s_barrier
	s_and_b64 vcc, exec, s[40:41]
	s_cbranch_vccnz .LBB0_759
	v_lshl_add_u64 v[0:1], v[0:1], 4, s[0:1]
	flat_load_dword v3, v[0:1] sc1
	flat_load_dword v4, v[0:1] offset:4 sc1
	flat_load_dword v5, v[0:1] offset:8 sc1
	flat_load_dword v6, v[0:1] offset:12 sc1
	s_waitcnt vmcnt(0) lgkmcnt(0)
	v_add_f32_e32 v3, 0, v3
	v_add_f32_e32 v3, v3, v4
	v_add_f32_e32 v3, v3, v5
	v_lshl_add_u32 v1, v2, 2, 0
	v_add_u32_e32 v1, 0x21000, v1
	v_add_f32_e32 v0, v3, v6
	v_fmamk_f32 v0, v0, 0x3a800000, v228
	v_rsq_f32_e32 v0, v0
	ds_write_b32 v1, v0

;     __device__ __forceinline__ void operator()(f32x4 (&acc)[2][2][4][2], const Unit& u, int wr, int wc, int fr_, int fq_) const {
;     ...
;                 for (int m = 0; m < 4; ++m)
; #pragma unroll
;                     for (int bj = 0; bj < 2; ++bj) { const u32x4 q = bsh[m][bj];
;                         acc[ai][bj][m][0] += (f32x4){__builtin_bit_cast(float, q.x << 16), __builtin_bit_cast(float, q.x & 0xffff0000u), __builtin_bit_cast(float, q.y << 16), __builtin_bit_cast(float, q.y & 0xffff0000u)};
;                         acc[ai][bj][m][1] += (f32x4){__builtin_bit_cast(float, q.z << 16), __builtin_bit_cast(float, q.z & 0xffff0000u), __builtin_bit_cast(float, q.w << 16), __builtin_bit_cast(float, q.w & 0xffff0000u)}; }
;                 asm volatile("" ::: "memory"); }
;         }
; #pragma unroll
;         for (int ai = 0; ai < 2; ++ai)
; #pragma unroll
;             for (int m = 0; m < 4; ++m) { float ss = 0.f;
; #pragma unroll
;                 for (int bj = 0; bj < 2; ++bj) { const f32x4 h0 = acc[ai][bj][m][0], h1 = acc[ai][bj][m][1];
;                     ss += ((h0[0] * h0[0] + h0[1] * h0[1]) + (h0[2] * h0[2] + h0[3] * h0[3])) + ((h1[0] * h1[0] + h1[1] * h1[1]) + (h1[2] * h1[2] + h1[3] * h1[3])); }
;                 ss += __builtin_bit_cast(float, __builtin_amdgcn_ds_bpermute((lane ^ 16) << 2, __builtin_bit_cast(int, ss)));
;                 ss += __builtin_bit_cast(float, __builtin_amdgcn_ds_bpermute((lane ^ 32) << 2, __builtin_bit_cast(int, ss)));
;                 if (fq == 0) P[(ai * HALF + wr * 64 + m * 16 + fr) * 4 + wc] = ss; }
.LBB0_979:
	s_or_b64 exec, exec, s[6:7]
	v_lshlrev_b32_e32 v170, 16, v164
	v_and_b32_e32 v171, 0xffff0000, v164
	s_waitcnt lgkmcnt(0)
	v_pk_add_f32 v[214:215], v[108:109], v[170:171]
	v_lshlrev_b32_e32 v108, 16, v166
	v_and_b32_e32 v109, 0xffff0000, v166
	v_lshlrev_b32_e32 v164, 16, v165
	v_and_b32_e32 v165, 0xffff0000, v165
	v_pk_add_f32 v[216:217], v[104:105], v[108:109]
	v_lshlrev_b32_e32 v104, 16, v160
	v_and_b32_e32 v105, 0xffff0000, v160
	v_pk_add_f32 v[164:165], v[110:111], v[164:165]
	v_lshlrev_b32_e32 v110, 16, v167
	v_and_b32_e32 v111, 0xffff0000, v167
	v_pk_add_f32 v[218:219], v[100:101], v[104:105]
	v_lshlrev_b32_e32 v100, 16, v162
	v_and_b32_e32 v101, 0xffff0000, v162
	v_pk_add_f32 v[166:167], v[106:107], v[110:111]
	v_lshlrev_b32_e32 v106, 16, v161
	v_and_b32_e32 v107, 0xffff0000, v161
	v_pk_add_f32 v[220:221], v[96:97], v[100:101]
	v_mul_f32_e32 v96, v215, v215
	v_mul_f32_e32 v97, v165, v165
	v_pk_add_f32 v[160:161], v[102:103], v[106:107]
	v_lshlrev_b32_e32 v102, 16, v163
	v_and_b32_e32 v103, 0xffff0000, v163
	v_fmac_f32_e32 v96, v214, v214
	v_fmac_f32_e32 v97, v164, v164
	v_pk_add_f32 v[162:163], v[98:99], v[102:103]
	v_add_f32_e32 v96, v96, v97
	v_mul_f32_e32 v97, v217, v217
	v_mul_f32_e32 v98, v167, v167
	v_fmac_f32_e32 v97, v216, v216
	v_fmac_f32_e32 v98, v166, v166
	v_add_f32_e32 v97, v97, v98
	v_add_f32_e32 v96, v96, v97
	v_mul_f32_e32 v97, v219, v219
	v_mul_f32_e32 v98, v161, v161
	v_fmac_f32_e32 v97, v218, v218
	v_fmac_f32_e32 v98, v160, v160
	v_add_f32_e32 v97, v97, v98
	v_mul_f32_e32 v98, v221, v221
	v_mul_f32_e32 v99, v163, v163
	v_fmac_f32_e32 v98, v220, v220
	v_fmac_f32_e32 v99, v162, v162
	v_add_f32_e32 v98, v98, v99
	v_add_f32_e32 v97, v97, v98
	v_add_f32_e32 v173, v96, v97
	v_lshlrev_b32_e32 v96, 16, v152
	s_waitcnt lgkmcnt(0)
	v_and_b32_e32 v97, 0xffff0000, v152
	v_lshlrev_b32_e32 v98, 16, v153
	v_and_b32_e32 v99, 0xffff0000, v153
	v_pk_add_f32 v[222:223], v[92:93], v[96:97]
	v_lshlrev_b32_e32 v92, 16, v154
	v_and_b32_e32 v93, 0xffff0000, v154
	v_pk_add_f32 v[152:153], v[94:95], v[98:99]
	v_lshlrev_b32_e32 v94, 16, v155
	v_and_b32_e32 v95, 0xffff0000, v155
	v_pk_add_f32 v[224:225], v[88:89], v[92:93]
	v_lshlrev_b32_e32 v88, 16, v144
	v_and_b32_e32 v89, 0xffff0000, v144
	v_pk_add_f32 v[154:155], v[90:91], v[94:95]
	v_lshlrev_b32_e32 v90, 16, v145
	v_and_b32_e32 v91, 0xffff0000, v145
	v_pk_add_f32 v[110:111], v[84:85], v[88:89]
	v_lshlrev_b32_e32 v84, 16, v146
	v_and_b32_e32 v85, 0xffff0000, v146
	v_pk_add_f32 v[108:109], v[86:87], v[90:91]
	v_pk_add_f32 v[90:91], v[80:81], v[84:85]
	v_mul_f32_e32 v80, v223, v223
	v_mul_f32_e32 v81, v153, v153
	v_lshlrev_b32_e32 v86, 16, v147
	v_and_b32_e32 v87, 0xffff0000, v147
	v_fmac_f32_e32 v80, v222, v222
	v_fmac_f32_e32 v81, v152, v152
	v_pk_add_f32 v[88:89], v[82:83], v[86:87]
	v_add_f32_e32 v80, v80, v81
	v_mul_f32_e32 v81, v225, v225
	v_mul_f32_e32 v82, v155, v155
	v_fmac_f32_e32 v81, v224, v224
	v_fmac_f32_e32 v82, v154, v154
	v_add_f32_e32 v81, v81, v82
	v_add_f32_e32 v80, v80, v81
	v_mul_f32_e32 v81, v111, v111
	v_mul_f32_e32 v82, v109, v109
	v_fmac_f32_e32 v81, v110, v110
	v_fmac_f32_e32 v82, v108, v108
	v_add_f32_e32 v81, v81, v82
	v_mul_f32_e32 v82, v91, v91
	v_mul_f32_e32 v83, v89, v89
	v_fmac_f32_e32 v82, v90, v90
	v_fmac_f32_e32 v83, v88, v88
	v_add_f32_e32 v82, v82, v83
	v_add_f32_e32 v81, v81, v82
	v_add_f32_e32 v178, v80, v81
	v_lshlrev_b32_e32 v80, 16, v136
	s_waitcnt lgkmcnt(0)
	v_and_b32_e32 v81, 0xffff0000, v136
	v_pk_add_f32 v[76:77], v[76:77], v[80:81]
	v_lshlrev_b32_e32 v80, 16, v138
	v_and_b32_e32 v81, 0xffff0000, v138
	v_lshlrev_b32_e32 v82, 16, v137
	v_and_b32_e32 v83, 0xffff0000, v137
	v_pk_add_f32 v[72:73], v[72:73], v[80:81]
	v_lshlrev_b32_e32 v80, 16, v128
	v_and_b32_e32 v81, 0xffff0000, v128
	v_pk_add_f32 v[78:79], v[78:79], v[82:83]
	v_lshlrev_b32_e32 v82, 16, v139
	v_and_b32_e32 v83, 0xffff0000, v139
	v_pk_add_f32 v[68:69], v[68:69], v[80:81]
	v_lshlrev_b32_e32 v80, 16, v130
	v_and_b32_e32 v81, 0xffff0000, v130
	v_pk_add_f32 v[74:75], v[74:75], v[82:83]
	v_lshlrev_b32_e32 v82, 16, v129
	v_and_b32_e32 v83, 0xffff0000, v129
	v_pk_add_f32 v[64:65], v[64:65], v[80:81]
	v_mul_f32_e32 v80, v77, v77
	v_mul_f32_e32 v81, v79, v79
	v_pk_add_f32 v[70:71], v[70:71], v[82:83]
	v_lshlrev_b32_e32 v82, 16, v131
	v_and_b32_e32 v83, 0xffff0000, v131
	v_fmac_f32_e32 v80, v76, v76
	v_fmac_f32_e32 v81, v78, v78
	v_pk_add_f32 v[66:67], v[66:67], v[82:83]
	v_add_f32_e32 v80, v80, v81
	v_mul_f32_e32 v81, v73, v73
	v_mul_f32_e32 v82, v75, v75
	v_fmac_f32_e32 v81, v72, v72
	v_fmac_f32_e32 v82, v74, v74
	v_add_f32_e32 v81, v81, v82
	v_add_f32_e32 v80, v80, v81
	v_mul_f32_e32 v81, v69, v69
	v_mul_f32_e32 v82, v71, v71
	v_fmac_f32_e32 v81, v68, v68
	v_fmac_f32_e32 v82, v70, v70
	v_add_f32_e32 v81, v81, v82
	v_mul_f32_e32 v82, v65, v65
	v_mul_f32_e32 v83, v67, v67
	v_fmac_f32_e32 v82, v64, v64
	v_fmac_f32_e32 v83, v66, v66
	v_add_f32_e32 v82, v82, v83
	v_add_f32_e32 v81, v81, v82
	v_add_f32_e32 v179, v80, v81
	s_waitcnt vmcnt(0)
	v_lshlrev_b32_e32 v80, 16, v156
	s_waitcnt lgkmcnt(0)
;     __device__ __forceinline__ void operator()(f32x4 (&acc)[2][2][4][2], const Unit& u, int wr, int wc, int fr_, int fq_) const {
;     ...
;                 for (int m = 0; m < 4; ++m)
; #pragma unroll
;                     for (int bj = 0; bj < 2; ++bj) { const u32x4 q = bsh[m][bj];
;                         acc[ai][bj][m][0] += (f32x4){__builtin_bit_cast(float, q.x << 16), __builtin_bit_cast(float, q.x & 0xffff0000u), __builtin_bit_cast(float, q.y << 16), __builtin_bit_cast(float, q.y & 0xffff0000u)};
;                         acc[ai][bj][m][1] += (f32x4){__builtin_bit_cast(float, q.z << 16), __builtin_bit_cast(float, q.z & 0xffff0000u), __builtin_bit_cast(float, q.w << 16), __builtin_bit_cast(float, q.w & 0xffff0000u)}; }
;                 asm volatile("" ::: "memory"); }
;         }
; #pragma unroll
;         for (int ai = 0; ai < 2; ++ai)
; #pragma unroll
;             for (int m = 0; m < 4; ++m) { float ss = 0.f;
; #pragma unroll
;                 for (int bj = 0; bj < 2; ++bj) { const f32x4 h0 = acc[ai][bj][m][0], h1 = acc[ai][bj][m][1];
;                     ss += ((h0[0] * h0[0] + h0[1] * h0[1]) + (h0[2] * h0[2] + h0[3] * h0[3])) + ((h1[0] * h1[0] + h1[1] * h1[1]) + (h1[2] * h1[2] + h1[3] * h1[3])); }
;                 ss += __builtin_bit_cast(float, __builtin_amdgcn_ds_bpermute((lane ^ 16) << 2, __builtin_bit_cast(int, ss)));
;                 ss += __builtin_bit_cast(float, __builtin_amdgcn_ds_bpermute((lane ^ 32) << 2, __builtin_bit_cast(int, ss)));
;                 if (fq == 0) P[(ai * HALF + wr * 64 + m * 16 + fr) * 4 + wc] = ss; }
	v_and_b32_e32 v81, 0xffff0000, v156
	v_pk_add_f32 v[60:61], v[60:61], v[80:81]
	v_lshlrev_b32_e32 v80, 16, v158
	v_and_b32_e32 v81, 0xffff0000, v158
	v_lshlrev_b32_e32 v82, 16, v157
	v_and_b32_e32 v83, 0xffff0000, v157
	v_pk_add_f32 v[56:57], v[56:57], v[80:81]
	v_lshlrev_b32_e32 v80, 16, v148
	v_and_b32_e32 v81, 0xffff0000, v148
	v_pk_add_f32 v[62:63], v[62:63], v[82:83]
	v_lshlrev_b32_e32 v82, 16, v159
	v_and_b32_e32 v83, 0xffff0000, v159
	v_pk_add_f32 v[52:53], v[52:53], v[80:81]
	v_lshlrev_b32_e32 v80, 16, v150
	v_and_b32_e32 v81, 0xffff0000, v150
	v_pk_add_f32 v[58:59], v[58:59], v[82:83]
	v_lshlrev_b32_e32 v82, 16, v149
	v_and_b32_e32 v83, 0xffff0000, v149
	v_pk_add_f32 v[48:49], v[48:49], v[80:81]
	v_mul_f32_e32 v80, v61, v61
	v_mul_f32_e32 v81, v63, v63
	v_pk_add_f32 v[54:55], v[54:55], v[82:83]
	v_lshlrev_b32_e32 v82, 16, v151
	v_and_b32_e32 v83, 0xffff0000, v151
	v_fmac_f32_e32 v80, v60, v60
	v_fmac_f32_e32 v81, v62, v62
	v_pk_add_f32 v[50:51], v[50:51], v[82:83]
	v_add_f32_e32 v80, v80, v81
	v_mul_f32_e32 v81, v57, v57
	v_mul_f32_e32 v82, v59, v59
	v_fmac_f32_e32 v81, v56, v56
	v_fmac_f32_e32 v82, v58, v58
	v_add_f32_e32 v81, v81, v82
	v_add_f32_e32 v80, v80, v81
	v_mul_f32_e32 v81, v53, v53
	v_mul_f32_e32 v82, v55, v55
	v_fmac_f32_e32 v81, v52, v52
	v_fmac_f32_e32 v82, v54, v54
	v_add_f32_e32 v81, v81, v82
	v_mul_f32_e32 v82, v49, v49
	v_mul_f32_e32 v83, v51, v51
	v_fmac_f32_e32 v82, v48, v48
	v_fmac_f32_e32 v83, v50, v50
	v_add_f32_e32 v82, v82, v83
	v_add_f32_e32 v81, v81, v82
	v_add_f32_e32 v244, v80, v81
	v_lshlrev_b32_e32 v80, 16, v140
	s_waitcnt lgkmcnt(0)
	v_and_b32_e32 v81, 0xffff0000, v140
	v_lshlrev_b32_e32 v82, 16, v141
	v_and_b32_e32 v83, 0xffff0000, v141
	v_pk_add_f32 v[46:47], v[46:47], v[82:83]
	v_pk_add_f32 v[44:45], v[44:45], v[80:81]
	v_lshlrev_b32_e32 v80, 16, v142
	v_and_b32_e32 v81, 0xffff0000, v142
	v_lshlrev_b32_e32 v82, 16, v143
	v_and_b32_e32 v83, 0xffff0000, v143
	v_pk_add_f32 v[42:43], v[42:43], v[82:83]
	v_pk_add_f32 v[82:83], v[40:41], v[80:81]
	v_lshlrev_b32_e32 v40, 16, v132
	v_and_b32_e32 v41, 0xffff0000, v132
	v_pk_add_f32 v[36:37], v[36:37], v[40:41]
	v_lshlrev_b32_e32 v40, 16, v134
	v_and_b32_e32 v41, 0xffff0000, v134
	v_lshlrev_b32_e32 v80, 16, v133
	v_and_b32_e32 v81, 0xffff0000, v133
	v_pk_add_f32 v[32:33], v[32:33], v[40:41]
	v_mul_f32_e32 v40, v45, v45
	v_mul_f32_e32 v41, v47, v47
	v_pk_add_f32 v[38:39], v[38:39], v[80:81]
	v_lshlrev_b32_e32 v80, 16, v135
	v_and_b32_e32 v81, 0xffff0000, v135
	v_fmac_f32_e32 v40, v44, v44
	v_fmac_f32_e32 v41, v46, v46
	v_pk_add_f32 v[34:35], v[34:35], v[80:81]
	v_add_f32_e32 v40, v40, v41
	v_mul_f32_e32 v41, v83, v83
	v_mul_f32_e32 v80, v43, v43
	v_fmac_f32_e32 v41, v82, v82
	v_fmac_f32_e32 v80, v42, v42
	v_add_f32_e32 v41, v41, v80
	v_add_f32_e32 v40, v40, v41
	v_mul_f32_e32 v41, v37, v37
	v_mul_f32_e32 v80, v39, v39
	v_fmac_f32_e32 v41, v36, v36
	v_fmac_f32_e32 v80, v38, v38
	v_add_f32_e32 v41, v41, v80
	v_mul_f32_e32 v80, v33, v33
	v_mul_f32_e32 v81, v35, v35
	v_fmac_f32_e32 v80, v32, v32
	v_fmac_f32_e32 v81, v34, v34
	v_add_f32_e32 v80, v80, v81
	v_add_f32_e32 v41, v41, v80
	v_add_f32_e32 v245, v40, v41
	v_lshlrev_b32_e32 v80, 16, v125
	v_and_b32_e32 v81, 0xffff0000, v125
	v_pk_add_f32 v[30:31], v[30:31], v[80:81]
	v_lshlrev_b32_e32 v80, 16, v127
	v_and_b32_e32 v81, 0xffff0000, v127
	v_lshlrev_b32_e32 v40, 16, v124
	s_waitcnt lgkmcnt(0)
;     __device__ __forceinline__ void operator()(f32x4 (&acc)[2][2][4][2], const Unit& u, int wr, int wc, int fr_, int fq_) const {
;     ...
;             for (int m = 0; m < 4; ++m) { float ss = 0.f;
; #pragma unroll
;                 for (int bj = 0; bj < 2; ++bj) { const f32x4 h0 = acc[ai][bj][m][0], h1 = acc[ai][bj][m][1];
;                     ss += ((h0[0] * h0[0] + h0[1] * h0[1]) + (h0[2] * h0[2] + h0[3] * h0[3])) + ((h1[0] * h1[0] + h1[1] * h1[1]) + (h1[2] * h1[2] + h1[3] * h1[3])); }
;                 ss += __builtin_bit_cast(float, __builtin_amdgcn_ds_bpermute((lane ^ 16) << 2, __builtin_bit_cast(int, ss)));
;                 ss += __builtin_bit_cast(float, __builtin_amdgcn_ds_bpermute((lane ^ 32) << 2, __builtin_bit_cast(int, ss)));
;                 if (fq == 0) P[(ai * HALF + wr * 64 + m * 16 + fr) * 4 + wc] = ss; }
	v_and_b32_e32 v41, 0xffff0000, v124
	v_pk_add_f32 v[84:85], v[26:27], v[80:81]
	v_lshlrev_b32_e32 v26, 16, v116
	v_and_b32_e32 v27, 0xffff0000, v116
	v_pk_add_f32 v[40:41], v[28:29], v[40:41]
	v_lshlrev_b32_e32 v28, 16, v126
	v_and_b32_e32 v29, 0xffff0000, v126
	v_pk_add_f32 v[26:27], v[20:21], v[26:27]
	v_lshlrev_b32_e32 v20, 16, v118
	v_and_b32_e32 v21, 0xffff0000, v118
	v_pk_add_f32 v[86:87], v[24:25], v[28:29]
	v_lshlrev_b32_e32 v24, 16, v117
	v_and_b32_e32 v25, 0xffff0000, v117
	v_pk_add_f32 v[80:81], v[16:17], v[20:21]
	v_mul_f32_e32 v16, v41, v41
	v_mul_f32_e32 v17, v31, v31
	v_pk_add_f32 v[24:25], v[22:23], v[24:25]
	v_lshlrev_b32_e32 v22, 16, v119
	v_and_b32_e32 v23, 0xffff0000, v119
	v_fmac_f32_e32 v16, v40, v40
	v_fmac_f32_e32 v17, v30, v30
	v_pk_add_f32 v[28:29], v[18:19], v[22:23]
	v_add_f32_e32 v16, v16, v17
	v_mul_f32_e32 v17, v87, v87
	v_mul_f32_e32 v18, v85, v85
	v_fmac_f32_e32 v17, v86, v86
	v_fmac_f32_e32 v18, v84, v84
	v_add_f32_e32 v17, v17, v18
	v_add_f32_e32 v16, v16, v17
	v_mul_f32_e32 v17, v27, v27
	v_mul_f32_e32 v18, v25, v25
	v_fmac_f32_e32 v17, v26, v26
	v_fmac_f32_e32 v18, v24, v24
	v_add_f32_e32 v17, v17, v18
	v_mul_f32_e32 v18, v81, v81
	v_mul_f32_e32 v19, v29, v29
	v_fmac_f32_e32 v18, v80, v80
	v_fmac_f32_e32 v19, v28, v28
	v_add_f32_e32 v18, v18, v19
	v_add_f32_e32 v17, v17, v18
	v_add_f32_e32 v246, v16, v17
	v_lshlrev_b32_e32 v16, 16, v120
	s_waitcnt lgkmcnt(0)
	v_and_b32_e32 v17, 0xffff0000, v120
	v_pk_add_f32 v[100:101], v[12:13], v[16:17]
	v_lshlrev_b32_e32 v12, 16, v122
	v_and_b32_e32 v13, 0xffff0000, v122
	v_lshlrev_b32_e32 v18, 16, v121
	v_and_b32_e32 v19, 0xffff0000, v121
	v_pk_add_f32 v[106:107], v[8:9], v[12:13]
	v_lshlrev_b32_e32 v8, 16, v112
	v_and_b32_e32 v9, 0xffff0000, v112
	v_pk_add_f32 v[96:97], v[14:15], v[18:19]
	v_lshlrev_b32_e32 v14, 16, v123
	v_and_b32_e32 v15, 0xffff0000, v123
	v_pk_add_f32 v[94:95], v[4:5], v[8:9]
	v_lshlrev_b32_e32 v4, 16, v114
	v_and_b32_e32 v5, 0xffff0000, v114
	v_pk_add_f32 v[104:105], v[10:11], v[14:15]
	v_lshlrev_b32_e32 v10, 16, v113
	v_and_b32_e32 v11, 0xffff0000, v113
	v_pk_add_f32 v[102:103], v[0:1], v[4:5]
	v_mul_f32_e32 v0, v101, v101
	v_mul_f32_e32 v1, v97, v97
	v_pk_add_f32 v[92:93], v[6:7], v[10:11]
	v_lshlrev_b32_e32 v6, 16, v115
	v_and_b32_e32 v7, 0xffff0000, v115
	v_fmac_f32_e32 v0, v100, v100
	v_fmac_f32_e32 v1, v96, v96
	v_pk_add_f32 v[98:99], v[2:3], v[6:7]
	v_add_f32_e32 v0, v0, v1
	v_mul_f32_e32 v1, v107, v107
	v_mul_f32_e32 v2, v105, v105
	v_fmac_f32_e32 v1, v106, v106
	v_fmac_f32_e32 v2, v104, v104
	v_add_f32_e32 v1, v1, v2
	v_add_f32_e32 v0, v0, v1
	v_mul_f32_e32 v1, v95, v95
	v_mul_f32_e32 v2, v93, v93
	v_fmac_f32_e32 v1, v94, v94
	v_fmac_f32_e32 v2, v92, v92
	v_add_f32_e32 v1, v1, v2
	v_mul_f32_e32 v2, v103, v103
	v_mul_f32_e32 v3, v99, v99
	v_fmac_f32_e32 v2, v102, v102
	v_fmac_f32_e32 v3, v98, v98
	v_add_f32_e32 v2, v2, v3
	v_add_f32_e32 v1, v1, v2
	v_add_f32_e32 v247, v0, v1
	ds_bpermute_b32 v170, v242, v173
	ds_bpermute_b32 v171, v242, v178
	ds_bpermute_b32 v172, v242, v179
	ds_bpermute_b32 v248, v242, v244
	ds_bpermute_b32 v249, v242, v245
	ds_bpermute_b32 v250, v242, v246
	ds_bpermute_b32 v251, v242, v247
	s_waitcnt lgkmcnt(0)
	v_add_f32_e32 v173, v173, v170
	v_add_f32_e32 v178, v178, v171
	v_add_f32_e32 v179, v179, v172
	v_add_f32_e32 v244, v244, v248
	v_add_f32_e32 v245, v245, v249
	v_add_f32_e32 v246, v246, v250
	v_add_f32_e32 v247, v247, v251
	ds_bpermute_b32 v170, v241, v173
	ds_bpermute_b32 v171, v241, v178
	ds_bpermute_b32 v172, v241, v179
	ds_bpermute_b32 v248, v241, v244
	ds_bpermute_b32 v249, v241, v245
	ds_bpermute_b32 v250, v241, v246
	ds_bpermute_b32 v251, v241, v247
	s_and_saveexec_b64 s[6:7], vcc
	s_cbranch_execz .LBB0_993
	s_waitcnt lgkmcnt(0)
	v_add_f32_e32 v173, v173, v170
	v_add_f32_e32 v178, v178, v171
	v_add_f32_e32 v179, v179, v172
	v_add_f32_e32 v244, v244, v248
	v_add_f32_e32 v245, v245, v249
	v_add_f32_e32 v246, v246, v250
	v_add_f32_e32 v247, v247, v251
	ds_write_b32 v243, v173 offset:256
	ds_write_b32 v243, v178 offset:512
	ds_write_b32 v243, v179 offset:768
	ds_write_b32 v243, v244 offset:2048
	ds_write_b32 v243, v245 offset:2304
	ds_write_b32 v243, v246 offset:2560
	ds_write_b32 v243, v247 offset:2816

;     __device__ __forceinline__ void operator()(f32x4 (&acc)[2][2][4][2], const Unit& u, int wr, int wc, int fr_, int fq_) const {
;     ...
;         if (wid < 4) {
;             const unsigned* slot = xbuf + (size_t)(u.pm * BM + tid) * 4; float s = 0.f;
; #pragma unroll
;             for (int q = 0; q < 4; ++q) s += __builtin_bit_cast(float, __hip_atomic_load(slot + q, __ATOMIC_RELAXED, __HIP_MEMORY_SCOPE_AGENT));
;             S[tid] = __builtin_amdgcn_rsqf(s * (1.0f / 1024.0f) + 1e-5f);
;         }
.LBB0_998:
	s_waitcnt vmcnt(0) lgkmcnt(0)
	s_barrier
	s_and_b64 vcc, exec, s[38:39]
	s_cbranch_vccnz .LBB0_1000
	v_lshl_add_u64 v[0:1], v[0:1], 4, s[0:1]
	flat_load_dword v3, v[0:1] sc1
	flat_load_dword v4, v[0:1] offset:4 sc1
	flat_load_dword v5, v[0:1] offset:8 sc1
	flat_load_dword v6, v[0:1] offset:12 sc1
	s_waitcnt vmcnt(0) lgkmcnt(0)
	v_add_f32_e32 v3, 0, v3
	v_add_f32_e32 v3, v3, v4
	v_add_f32_e32 v3, v3, v5
	v_lshl_add_u32 v1, v2, 2, 0
	v_add_u32_e32 v1, 0x21000, v1
	v_add_f32_e32 v0, v3, v6
	v_fmamk_f32 v0, v0, 0x3a800000, v228
	v_rsq_f32_e32 v0, v0
	ds_write_b32 v1, v0
